# EpiMix A-head qk-norm: gamma vectors for offsets 0/16 loaded once per tile and kept in VGPRs (14 serialized load+vmcnt(0) round trips per tile removed)
# speedup vs baseline: 1.0052x; 1.0052x over previous
;     __device__ __forceinline__ void operator()(const f32x4 (&acc)[2][2][4][2], const Unit& u, int wr, int wc, int fr, int fq) const {
;     ...
;         if (u.pn <= 1) {
;             const int slot = u.pn * 4 + wc; const bool isq = slot < 6;
;             const float* g = isq ? gq : gk;
;             bf16_t* dst = isq ? (bf16_t*)(mx + MX_QA) + (size_t)slot * R * 64 : (bf16_t*)(mx + MX_KA) + (size_t)(slot - 6) * R * 64;
;             float fr0[2], fr1[2];
; #pragma unroll
;             for (int n = 0; n < 2; ++n) { const float p = (float)(4 * fq + 2 * n);
;                 fr0[n] = fast_exp2(-p * (13.287712379549449f / 16.0f)) * 0.15915494309189535f; fr1[n] = fast_exp2(-(p + 1.0f) * (13.287712379549449f / 16.0f)) * 0.15915494309189535f; }
; #pragma unroll
;             for (int ai = 0; ai < 2; ++ai)
; #pragma unroll
;                 for (int m = 0; m < 4; ++m) {
;                     const int row = row0 + ai * HALF + m * 16;
;                     int fqo = fq; asm volatile("" : "+v"(fqo));
;                     f32x4 v[2][2]; float ss = 0.f;
; #pragma unroll
;                     for (int bj = 0; bj < 2; ++bj)
; #pragma unroll
;                         for (int n = 0; n < 2; ++n) { v[bj][n] = acc[ai][bj][m][n]; ss += (v[bj][n][0] * v[bj][n][0] + v[bj][n][1] * v[bj][n][1]) + (v[bj][n][2] * v[bj][n][2] + v[bj][n][3] * v[bj][n][3]); }
;                     ss += swz_xor<16>(ss); ss = xadd32(ss);
;                     const float rstd = __builtin_amdgcn_rsqf(ss * (1.0f / 64.0f) + EPS);
;                     const int t = row & (SEQ - 1); const float pos[2] = {(float)(t >> 6), (float)(t & 63)};
; #pragma unroll
;                     for (int bj = 0; bj < 2; ++bj) {
;                         u32x4 w;
; #pragma unroll
;                         for (int n = 0; n < 2; ++n) {
;                             f32x4 x = v[bj][n] * rstd * *(const f32x4*)(g + 32 * bj + 8 * fqo + 4 * n);
;                             if (latent) {
;                                 const float a0 = pos[bj] * fr0[n], a1 = pos[bj] * fr1[n];
;                                 const float c0 = __builtin_amdgcn_cosf(a0), s0 = __builtin_amdgcn_sinf(a0), c1 = __builtin_amdgcn_cosf(a1), s1 = __builtin_amdgcn_sinf(a1);
;                                 x = (f32x4){x[0] * c0 - x[1] * s0, x[1] * c0 + x[0] * s0, x[2] * c1 - x[3] * s1, x[3] * c1 + x[2] * s1};
;                             }
.LBB0_452:
	s_andn2_b64 vcc, exec, s[0:1]
	s_cbranch_vccnz .LBB0_518
	v_lshlrev_b32_e32 v141, 2, v236
	v_cvt_f32_i32_e32 v142, v141
	v_mul_f32_e32 v144, v124, v124
	v_mul_f32_e32 v145, v125, v125
	s_lshl_b32 s0, s42, 2
	s_or_b32 s15, s0, s76
	v_mul_f32_e32 v143, 0xbf549a78, v142
	v_add_f32_e32 v142, 1.0, v142
	v_mul_f32_e32 v142, 0xbf549a78, v142
	v_exp_f32_e32 v143, v143
	v_exp_f32_e32 v142, v142
	s_cmp_lt_i32 s15, 6
	s_cselect_b64 s[0:1], -1, 0
	v_mul_f32_e32 v194, 0.15915494, v143
	v_mul_f32_e32 v237, 0.15915494, v142
	v_mul_f32_e32 v142, v126, v126
	v_mul_f32_e32 v143, v127, v127
	v_mov_b32_e32 v151, v236
	v_pk_mov_b32 v[146:147], v[144:145], v[142:143] op_sel:[1,0]
	v_mov_b32_e32 v145, v143
	v_add_f32_e32 v142, v146, v144
	v_add_f32_e32 v143, v147, v145
	v_mul_f32_e32 v144, v122, v122
	v_mul_f32_e32 v145, v123, v123
	v_mul_f32_e32 v146, v120, v120
	v_mul_f32_e32 v147, v121, v121
	v_pk_add_f32 v[142:143], v[142:143], v[142:143] op_sel:[0,1] op_sel_hi:[1,0]
	v_pk_mov_b32 v[148:149], v[146:147], v[144:145] op_sel:[1,0]
	v_mov_b32_e32 v147, v145
	v_add_f32_e32 v144, v148, v146
	v_add_f32_e32 v145, v149, v147
	v_mul_f32_e32 v146, v104, v104
	v_mul_f32_e32 v147, v105, v105
	v_pk_add_f32 v[144:145], v[144:145], v[144:145] op_sel:[0,1] op_sel_hi:[1,0]
	v_mov_b32_e32 v143, v146
	v_mov_b32_e32 v145, v147
	v_add_f32_e32 v142, v142, v144
	v_add_f32_e32 v143, v143, v145
	v_mul_f32_e32 v144, v109, v109
	v_mul_f32_e32 v146, v111, v111
	v_mul_f32_e32 v148, v106, v106
	v_mul_f32_e32 v149, v107, v107
	v_fma_f32 v145, v109, v109, v144
	v_fma_f32 v144, v108, v108, v144
	v_fma_f32 v147, v111, v111, v146
	v_fma_f32 v146, v110, v110, v146
	v_mov_b32_e32 v145, v148
	v_mov_b32_e32 v147, v149
	v_add_f32_e32 v144, v144, v146
	v_add_f32_e32 v145, v145, v147
	s_and_b64 s[36:37], s[0:1], exec
	v_add_f32_e32 v142, v142, v144
	v_add_f32_e32 v143, v143, v145
	s_cselect_b32 s39, s73, s75
	v_add_f32_e32 v142, v142, v143
	ds_swizzle_b32 v143, v142 offset:swizzle(SWAP,16)
	s_cselect_b32 s38, s72, s74
	s_andn2_b64 vcc, exec, s[18:19]
	s_waitcnt lgkmcnt(0)
	v_add_f32_e32 v142, v142, v143
	v_mov_b32_e32 v143, v142
	s_nop 1
	v_permlane32_swap_b32_e32 v142, v143
	v_add_f32_e32 v142, v142, v143
	v_fmamk_f32 v142, v142, 0x3c800000, v193
	v_rsq_f32_e32 v150, v142
	v_bfe_u32 v142, v140, 6, 7
	v_cvt_f32_ubyte0_e32 v156, v142
	v_lshlrev_b32_e32 v142, 3, v151
	v_ashrrev_i32_e32 v143, 31, v142
	v_lshl_add_u64 v[152:153], v[142:143], 2, s[38:39]
	global_load_dwordx4 v[142:145], v[152:153], off
	v_mul_f32_e32 v146, v124, v150
	v_mul_f32_e32 v147, v125, v150
	v_mul_f32_e32 v148, v126, v150
	v_mul_f32_e32 v149, v127, v150
	s_waitcnt vmcnt(0)
	v_mov_b32_e32 v246, v142
	v_mov_b32_e32 v247, v143
	v_mov_b32_e32 v248, v144
	v_mov_b32_e32 v249, v145
	v_mul_f32_e32 v142, v142, v146
	v_mul_f32_e32 v143, v143, v147
	v_cndmask_b32_e64 v146, 0, 1, s[18:19]
	v_mul_f32_e32 v144, v144, v148
	v_mul_f32_e32 v145, v145, v149
	v_cmp_ne_u32_e64 s[36:37], 1, v146
	s_cbranch_vccnz .LBB0_455
	v_mul_f32_e32 v147, v194, v156
	v_sin_f32_e32 v148, v147
	v_mul_f32_e32 v149, v237, v156
	v_cos_f32_e32 v146, v147
	v_sin_f32_e32 v155, v149
	v_cos_f32_e32 v154, v149
	v_mul_f32_e32 v149, v148, v142
	v_mul_f32_e32 v148, v148, v143
	v_mul_f32_e32 v158, v146, v142
	v_mul_f32_e32 v159, v146, v143
	v_fma_f32 v142, v146, v142, v148
	v_fma_f32 v143, v146, v143, v149
	v_mul_f32_e32 v142, v155, v145
	v_fma_f32 v146, v154, v144, -v142
	v_fma_f32 v147, v155, v145, -v142
	v_mov_b32_e32 v160, v155
	v_mov_b32_e32 v161, v154
	v_mul_f32_e32 v142, v154, v145
	v_fma_f32 v154, v160, v144, v142
	v_fma_f32 v155, v161, v145, v142
	v_sub_f32_e32 v142, v158, v148
	v_mov_b32_e32 v144, v146
	v_mov_b32_e32 v145, v154
.LBB0_455:
	global_load_dwordx4 v[158:161], v[152:153], off offset:16
	v_or_b32_e32 v141, 2, v141
	v_cvt_f32_i32_e32 v141, v141
	v_mov_b32_e32 v151, v150
	v_mov_b32_e32 v146, v150
	v_mov_b32_e32 v147, v150
	v_mul_f32_e32 v148, 0xbf549a78, v141
	v_add_f32_e32 v141, 1.0, v141
	v_mul_f32_e32 v141, 0xbf549a78, v141
	v_exp_f32_e32 v154, v148
	v_exp_f32_e32 v141, v141
	v_mul_f32_e32 v148, v122, v146
	v_mul_f32_e32 v149, v123, v147
	v_mul_f32_e32 v162, v120, v150
	v_mul_f32_e32 v163, v121, v151
	s_and_b64 vcc, exec, s[36:37]
	v_mul_f32_e32 v238, 0.15915494, v154
	v_mul_f32_e32 v239, 0.15915494, v141
	s_waitcnt vmcnt(0)
	v_mov_b32_e32 v250, v158
	v_mov_b32_e32 v251, v159
	v_mov_b32_e32 v200, v160
	v_mov_b32_e32 v201, v161
	v_mul_f32_e32 v154, v148, v160
	v_mul_f32_e32 v155, v149, v161
	v_mul_f32_e32 v148, v162, v158
	v_mul_f32_e32 v149, v163, v159
	s_cbranch_vccnz .LBB0_457
	v_mul_f32_e32 v141, v238, v156
	v_sin_f32_e32 v158, v141
	v_mul_f32_e32 v157, v239, v156
	v_cos_f32_e32 v156, v141
	v_sin_f32_e32 v161, v157
	v_cos_f32_e32 v160, v157
	v_mul_f32_e32 v159, v158, v148
	v_mul_f32_e32 v158, v158, v149
	v_mul_f32_e32 v162, v156, v148
	v_mul_f32_e32 v163, v156, v149
	v_fma_f32 v148, v156, v148, v158
	v_fma_f32 v149, v156, v149, v159
	v_mul_f32_e32 v148, v161, v155
	v_fma_f32 v156, v160, v154, -v148
	v_fma_f32 v157, v161, v155, -v148
	v_mov_b32_e32 v164, v161
	v_mov_b32_e32 v165, v160
	v_mul_f32_e32 v148, v160, v155
	v_fma_f32 v160, v164, v154, v148
	v_fma_f32 v161, v165, v155, v148
	v_sub_f32_e32 v148, v162, v158
	v_mov_b32_e32 v154, v156
	v_mov_b32_e32 v155, v160

; __device__ __forceinline__ unsigned cvt_pk_bf16(float lo, float hi) { const f32x2 v = {lo, hi}; const bf16x2_t b = __builtin_convertvector(v, bf16x2_t); return __builtin_bit_cast(unsigned, b); }
; template <int M> __device__ __forceinline__ float swz_xor(float v) { return __builtin_bit_cast(float, __builtin_amdgcn_ds_swizzle(__builtin_bit_cast(int, v), (M << 10) | 0x1f)); }
;     __device__ __forceinline__ void operator()(const f32x4 (&acc)[2][2][4][2], const Unit& u, int wr, int wc, int fr, int fq) const {
;     ...
;                     const int row = row0 + ai * HALF + m * 16;
;                     int fqo = fq; asm volatile("" : "+v"(fqo));
;                     f32x4 v[2][2]; float ss = 0.f;
; #pragma unroll
;                     for (int bj = 0; bj < 2; ++bj)
; #pragma unroll
;                         for (int n = 0; n < 2; ++n) { v[bj][n] = acc[ai][bj][m][n]; ss += (v[bj][n][0] * v[bj][n][0] + v[bj][n][1] * v[bj][n][1]) + (v[bj][n][2] * v[bj][n][2] + v[bj][n][3] * v[bj][n][3]); }
;                     ss += swz_xor<16>(ss); ss = xadd32(ss);
;                     const float rstd = __builtin_amdgcn_rsqf(ss * (1.0f / 64.0f) + EPS);
;                     const int t = row & (SEQ - 1); const float pos[2] = {(float)(t >> 6), (float)(t & 63)};
; #pragma unroll
;                     for (int bj = 0; bj < 2; ++bj) {
;                         u32x4 w;
; #pragma unroll
;                         for (int n = 0; n < 2; ++n) {
;                             f32x4 x = v[bj][n] * rstd * *(const f32x4*)(g + 32 * bj + 8 * fqo + 4 * n);
;                             if (latent) {
;                                 const float a0 = pos[bj] * fr0[n], a1 = pos[bj] * fr1[n];
;                                 const float c0 = __builtin_amdgcn_cosf(a0), s0 = __builtin_amdgcn_sinf(a0), c1 = __builtin_amdgcn_cosf(a1), s1 = __builtin_amdgcn_sinf(a1);
;                                 x = (f32x4){x[0] * c0 - x[1] * s0, x[1] * c0 + x[0] * s0, x[2] * c1 - x[3] * s1, x[3] * c1 + x[2] * s1};
;                             }
;                             if (n == 0) { w.x = cvt_pk_bf16(x[0], x[1]); w.y = cvt_pk_bf16(x[2], x[3]); } else { w.z = cvt_pk_bf16(x[0], x[1]); w.w = cvt_pk_bf16(x[2], x[3]); }
;                         }
;                         *(u32x4*)(dst + (size_t)row * 64 + 32 * bj + 8 * fq) = w;
.LBB0_461:
	v_cvt_pk_bf16_f32 v158, v158, v159
	v_cvt_pk_bf16_f32 v159, v160, v161
	v_cvt_pk_bf16_f32 v160, v162, v163
	v_cvt_pk_bf16_f32 v161, v164, v165
	global_store_dwordx4 v[156:157], v[158:161], off offset:64
	v_mul_f32_e32 v156, v118, v118
	v_mul_f32_e32 v157, v119, v119
	s_nop 0
	v_mul_f32_e32 v158, v116, v116
	v_mul_f32_e32 v159, v117, v117
	v_mul_f32_e32 v141, v88, v88
	v_pk_mov_b32 v[160:161], v[158:159], v[156:157] op_sel:[1,0]
	v_mov_b32_e32 v159, v157
	v_add_f32_e32 v156, v160, v158
	v_add_f32_e32 v157, v161, v159
	v_mul_f32_e32 v158, v114, v114
	v_mul_f32_e32 v159, v115, v115
	v_mul_f32_e32 v160, v112, v112
	v_mul_f32_e32 v161, v113, v113
	v_mul_f32_e32 v149, v89, v89
	v_pk_mov_b32 v[162:163], v[160:161], v[158:159] op_sel:[1,0]
	v_mov_b32_e32 v161, v159
	v_add_f32_e32 v158, v162, v160
	v_add_f32_e32 v159, v163, v161
	v_pk_add_f32 v[156:157], v[156:157], v[156:157] op_sel:[0,1] op_sel_hi:[1,0]
	v_pk_add_f32 v[158:159], v[158:159], v[158:159] op_sel:[0,1] op_sel_hi:[1,0]
	v_mov_b32_e32 v157, v141
	v_mov_b32_e32 v159, v149
	v_add_f32_e32 v156, v156, v158
	v_add_f32_e32 v157, v157, v159
	v_mul_f32_e32 v158, v93, v93
	v_mul_f32_e32 v160, v95, v95
	v_mul_f32_e32 v153, v90, v90
	v_mul_f32_e32 v155, v91, v91
	v_fma_f32 v159, v93, v93, v158
	v_fma_f32 v158, v92, v92, v158
	v_fma_f32 v161, v95, v95, v160
	v_fma_f32 v160, v94, v94, v160
	v_mov_b32_e32 v159, v153
	v_mov_b32_e32 v161, v155
	v_mov_b32_e32 v147, v236
	v_add_f32_e32 v158, v158, v160
	v_add_f32_e32 v159, v159, v161
	s_and_b64 vcc, exec, s[36:37]
	v_add_f32_e32 v156, v156, v158
	v_add_f32_e32 v157, v157, v159
	v_lshlrev_b32_e32 v158, 3, v147
	v_ashrrev_i32_e32 v159, 31, v158
	v_lshl_add_u64 v[164:165], v[158:159], 2, s[38:39]
	v_mov_b32_e32 v158, v246
	v_mov_b32_e32 v159, v247
	v_mov_b32_e32 v160, v248
	v_mov_b32_e32 v161, v249
	v_add_f32_e32 v141, v156, v157
	ds_swizzle_b32 v149, v141 offset:swizzle(SWAP,16)
	v_add_u32_e32 v156, 16, v140
	s_waitcnt lgkmcnt(0)
	v_add_f32_e32 v141, v141, v149
	v_mov_b32_e32 v149, v141
	s_nop 1
	v_permlane32_swap_b32_e32 v141, v149
	v_add_f32_e32 v141, v141, v149
	v_fmamk_f32 v141, v141, 0x3c800000, v193
	v_rsq_f32_e32 v162, v141
	v_bfe_u32 v141, v156, 6, 7
	v_cvt_f32_ubyte0_e32 v141, v141
	v_mul_f32_e32 v166, v116, v162
	v_mul_f32_e32 v167, v117, v162
	v_mul_f32_e32 v168, v118, v162
	v_mul_f32_e32 v169, v119, v162
	v_mul_f32_e32 v158, v158, v166
	v_mul_f32_e32 v159, v159, v167
	v_mul_f32_e32 v160, v160, v168
	v_mul_f32_e32 v161, v161, v169
	s_cbranch_vccnz .LBB0_463
	v_mul_f32_e32 v147, v194, v141
	v_sin_f32_e32 v168, v147
	v_mul_f32_e32 v149, v237, v141
	v_cos_f32_e32 v166, v147
	v_sin_f32_e32 v171, v149
	v_cos_f32_e32 v170, v149
	v_mul_f32_e32 v169, v168, v158
	v_mul_f32_e32 v168, v168, v159
	v_mul_f32_e32 v172, v166, v158
	v_mul_f32_e32 v173, v166, v159
	v_fma_f32 v158, v166, v158, v168
	v_fma_f32 v159, v166, v159, v169
	v_mul_f32_e32 v158, v171, v161
	v_fma_f32 v166, v170, v160, -v158
	v_fma_f32 v167, v171, v161, -v158
	v_mov_b32_e32 v174, v171
	v_mov_b32_e32 v175, v170
	v_mul_f32_e32 v158, v170, v161
	v_fma_f32 v170, v174, v160, v158
	v_fma_f32 v171, v175, v161, v158
	v_sub_f32_e32 v158, v172, v168
	v_mov_b32_e32 v160, v166
	v_mov_b32_e32 v161, v170
.LBB0_463:
	v_mov_b32_e32 v168, v250
	v_mov_b32_e32 v169, v251
	v_mov_b32_e32 v170, v200
	v_mov_b32_e32 v171, v201
	v_mov_b32_e32 v163, v162
	v_mov_b32_e32 v166, v162
	v_mov_b32_e32 v167, v162
	v_mul_f32_e32 v172, v114, v166
	v_mul_f32_e32 v173, v115, v167
	v_mul_f32_e32 v174, v112, v162
	v_mul_f32_e32 v175, v113, v163
	s_and_b64 vcc, exec, s[36:37]
	v_mul_f32_e32 v172, v172, v170
	v_mul_f32_e32 v173, v173, v171
	v_mul_f32_e32 v170, v174, v168
	v_mul_f32_e32 v171, v175, v169
	s_cbranch_vccnz .LBB0_465
	v_mul_f32_e32 v147, v238, v141
	v_sin_f32_e32 v174, v147
	v_mul_f32_e32 v141, v239, v141
	v_cos_f32_e32 v168, v147
	v_cos_f32_e32 v176, v141
	v_sin_f32_e32 v177, v141
	v_mul_f32_e32 v175, v174, v170
	v_mul_f32_e32 v174, v174, v171
	v_mul_f32_e32 v178, v168, v170
	v_mul_f32_e32 v179, v168, v171
	v_fma_f32 v170, v168, v170, v174
	v_fma_f32 v171, v168, v171, v175
	v_mul_f32_e32 v168, v177, v173
	v_mov_b32_e32 v182, v177
	v_mov_b32_e32 v183, v176
	v_mul_f32_e32 v170, v176, v173
	v_fma_f32 v169, v177, v173, -v168
	v_fma_f32 v168, v176, v172, -v168
	v_fma_f32 v176, v182, v172, v170
	v_fma_f32 v177, v183, v173, v170
	v_sub_f32_e32 v170, v178, v174
	v_mov_b32_e32 v172, v168
	v_mov_b32_e32 v173, v176

; __device__ __forceinline__ unsigned cvt_pk_bf16(float lo, float hi) { const f32x2 v = {lo, hi}; const bf16x2_t b = __builtin_convertvector(v, bf16x2_t); return __builtin_bit_cast(unsigned, b); }
; template <int M> __device__ __forceinline__ float swz_xor(float v) { return __builtin_bit_cast(float, __builtin_amdgcn_ds_swizzle(__builtin_bit_cast(int, v), (M << 10) | 0x1f)); }
;     __device__ __forceinline__ void operator()(const f32x4 (&acc)[2][2][4][2], const Unit& u, int wr, int wc, int fr, int fq) const {
;     ...
;                     const int row = row0 + ai * HALF + m * 16;
;                     int fqo = fq; asm volatile("" : "+v"(fqo));
;                     f32x4 v[2][2]; float ss = 0.f;
; #pragma unroll
;                     for (int bj = 0; bj < 2; ++bj)
; #pragma unroll
;                         for (int n = 0; n < 2; ++n) { v[bj][n] = acc[ai][bj][m][n]; ss += (v[bj][n][0] * v[bj][n][0] + v[bj][n][1] * v[bj][n][1]) + (v[bj][n][2] * v[bj][n][2] + v[bj][n][3] * v[bj][n][3]); }
;                     ss += swz_xor<16>(ss); ss = xadd32(ss);
;                     const float rstd = __builtin_amdgcn_rsqf(ss * (1.0f / 64.0f) + EPS);
;                     const int t = row & (SEQ - 1); const float pos[2] = {(float)(t >> 6), (float)(t & 63)};
; #pragma unroll
;                     for (int bj = 0; bj < 2; ++bj) {
;                         u32x4 w;
; #pragma unroll
;                         for (int n = 0; n < 2; ++n) {
;                             f32x4 x = v[bj][n] * rstd * *(const f32x4*)(g + 32 * bj + 8 * fqo + 4 * n);
;                             if (latent) {
;                                 const float a0 = pos[bj] * fr0[n], a1 = pos[bj] * fr1[n];
;                                 const float c0 = __builtin_amdgcn_cosf(a0), s0 = __builtin_amdgcn_sinf(a0), c1 = __builtin_amdgcn_cosf(a1), s1 = __builtin_amdgcn_sinf(a1);
;                                 x = (f32x4){x[0] * c0 - x[1] * s0, x[1] * c0 + x[0] * s0, x[2] * c1 - x[3] * s1, x[3] * c1 + x[2] * s1};
;                             }
;                             if (n == 0) { w.x = cvt_pk_bf16(x[0], x[1]); w.y = cvt_pk_bf16(x[2], x[3]); } else { w.z = cvt_pk_bf16(x[0], x[1]); w.w = cvt_pk_bf16(x[2], x[3]); }
;                         }
;                         *(u32x4*)(dst + (size_t)row * 64 + 32 * bj + 8 * fq) = w;
.LBB0_469:
	v_cvt_pk_bf16_f32 v170, v170, v171
	v_cvt_pk_bf16_f32 v171, v172, v173
	v_cvt_pk_bf16_f32 v172, v174, v175
	v_cvt_pk_bf16_f32 v173, v176, v177
	global_store_dwordx4 v[168:169], v[170:173], off offset:64
	v_mul_f32_e32 v168, v102, v102
	v_mul_f32_e32 v169, v103, v103
	s_nop 0
	v_mul_f32_e32 v170, v100, v100
	v_mul_f32_e32 v171, v101, v101
	v_mul_f32_e32 v141, v72, v72
	v_pk_mov_b32 v[172:173], v[170:171], v[168:169] op_sel:[1,0]
	v_mov_b32_e32 v171, v169
	v_add_f32_e32 v168, v172, v170
	v_add_f32_e32 v169, v173, v171
	v_mul_f32_e32 v170, v98, v98
	v_mul_f32_e32 v171, v99, v99
	v_mul_f32_e32 v172, v96, v96
	v_mul_f32_e32 v173, v97, v97
	v_mul_f32_e32 v149, v73, v73
	v_pk_mov_b32 v[174:175], v[172:173], v[170:171] op_sel:[1,0]
	v_mov_b32_e32 v173, v171
	v_add_f32_e32 v170, v174, v172
	v_add_f32_e32 v171, v175, v173
	v_pk_add_f32 v[168:169], v[168:169], v[168:169] op_sel:[0,1] op_sel_hi:[1,0]
	v_pk_add_f32 v[170:171], v[170:171], v[170:171] op_sel:[0,1] op_sel_hi:[1,0]
	v_mov_b32_e32 v169, v141
	v_mov_b32_e32 v171, v149
	v_add_f32_e32 v168, v168, v170
	v_add_f32_e32 v169, v169, v171
	v_mul_f32_e32 v170, v77, v77
	v_mul_f32_e32 v172, v79, v79
	v_mul_f32_e32 v153, v74, v74
	v_mul_f32_e32 v155, v75, v75
	v_fma_f32 v171, v77, v77, v170
	v_fma_f32 v170, v76, v76, v170
	v_fma_f32 v173, v79, v79, v172
	v_fma_f32 v172, v78, v78, v172
	v_mov_b32_e32 v171, v153
	v_mov_b32_e32 v173, v155
	v_mov_b32_e32 v147, v236
	v_add_f32_e32 v170, v170, v172
	v_add_f32_e32 v171, v171, v173
	s_and_b64 vcc, exec, s[36:37]
	v_add_f32_e32 v168, v168, v170
	v_add_f32_e32 v169, v169, v171
	v_lshlrev_b32_e32 v170, 3, v147
	v_ashrrev_i32_e32 v171, 31, v170
	v_lshl_add_u64 v[176:177], v[170:171], 2, s[38:39]
	v_mov_b32_e32 v170, v246
	v_mov_b32_e32 v171, v247
	v_mov_b32_e32 v172, v248
	v_mov_b32_e32 v173, v249
	v_add_f32_e32 v141, v168, v169
	ds_swizzle_b32 v149, v141 offset:swizzle(SWAP,16)
	v_add_u32_e32 v168, 32, v140
	s_waitcnt lgkmcnt(0)
	v_add_f32_e32 v141, v141, v149
	v_mov_b32_e32 v149, v141
	s_nop 1
	v_permlane32_swap_b32_e32 v141, v149
	v_add_f32_e32 v141, v141, v149
	v_fmamk_f32 v141, v141, 0x3c800000, v193
	v_rsq_f32_e32 v174, v141
	v_bfe_u32 v141, v168, 6, 7
	v_cvt_f32_ubyte0_e32 v141, v141
	v_mul_f32_e32 v178, v100, v174
	v_mul_f32_e32 v179, v101, v174
	v_mul_f32_e32 v182, v102, v174
	v_mul_f32_e32 v183, v103, v174
	v_mul_f32_e32 v170, v170, v178
	v_mul_f32_e32 v171, v171, v179
	v_mul_f32_e32 v172, v172, v182
	v_mul_f32_e32 v173, v173, v183
	s_cbranch_vccnz .LBB0_471
	v_mul_f32_e32 v147, v194, v141
	v_sin_f32_e32 v182, v147
	v_mul_f32_e32 v149, v237, v141
	v_cos_f32_e32 v178, v147
	v_sin_f32_e32 v185, v149
	v_cos_f32_e32 v184, v149
	v_mul_f32_e32 v183, v182, v170
	v_mul_f32_e32 v182, v182, v171
	v_mul_f32_e32 v186, v178, v170
	v_mul_f32_e32 v187, v178, v171
	v_fma_f32 v170, v178, v170, v182
	v_fma_f32 v171, v178, v171, v183
	v_mul_f32_e32 v170, v185, v173
	v_fma_f32 v178, v184, v172, -v170
	v_fma_f32 v179, v185, v173, -v170
	v_mov_b32_e32 v188, v185
	v_mov_b32_e32 v189, v184
	v_mul_f32_e32 v170, v184, v173
	v_fma_f32 v184, v188, v172, v170
	v_fma_f32 v185, v189, v173, v170
	v_sub_f32_e32 v170, v186, v182
	v_mov_b32_e32 v172, v178
	v_mov_b32_e32 v173, v184
.LBB0_471:
	v_mov_b32_e32 v182, v250
	v_mov_b32_e32 v183, v251
	v_mov_b32_e32 v184, v200
	v_mov_b32_e32 v185, v201
	v_mov_b32_e32 v175, v174
	v_mov_b32_e32 v178, v174
	v_mov_b32_e32 v179, v174
	v_mul_f32_e32 v186, v98, v178
	v_mul_f32_e32 v187, v99, v179
	v_mul_f32_e32 v188, v96, v174
	v_mul_f32_e32 v189, v97, v175
	s_and_b64 vcc, exec, s[36:37]
	v_mul_f32_e32 v184, v186, v184
	v_mul_f32_e32 v185, v187, v185
	v_mul_f32_e32 v182, v188, v182
	v_mul_f32_e32 v183, v189, v183
	s_cbranch_vccnz .LBB0_473
	v_mul_f32_e32 v147, v238, v141
	v_sin_f32_e32 v188, v147
	v_mul_f32_e32 v141, v239, v141
	v_cos_f32_e32 v186, v147
	v_sin_f32_e32 v191, v141
	v_cos_f32_e32 v190, v141
	v_mul_f32_e32 v189, v188, v182
	v_mul_f32_e32 v188, v188, v183
	v_mul_f32_e32 v208, v186, v182
	v_mul_f32_e32 v209, v186, v183
	v_fma_f32 v182, v186, v182, v188
	v_fma_f32 v183, v186, v183, v189
	v_mul_f32_e32 v182, v191, v185
	v_fma_f32 v186, v190, v184, -v182
	v_fma_f32 v187, v191, v185, -v182
	v_mov_b32_e32 v210, v191
	v_mov_b32_e32 v211, v190
	v_mul_f32_e32 v182, v190, v185
	v_fma_f32 v190, v210, v184, v182
	v_fma_f32 v191, v211, v185, v182
	v_sub_f32_e32 v182, v208, v188
	v_mov_b32_e32 v184, v186
	v_mov_b32_e32 v185, v190

; __device__ __forceinline__ unsigned cvt_pk_bf16(float lo, float hi) { const f32x2 v = {lo, hi}; const bf16x2_t b = __builtin_convertvector(v, bf16x2_t); return __builtin_bit_cast(unsigned, b); }
; template <int M> __device__ __forceinline__ float swz_xor(float v) { return __builtin_bit_cast(float, __builtin_amdgcn_ds_swizzle(__builtin_bit_cast(int, v), (M << 10) | 0x1f)); }
;     __device__ __forceinline__ void operator()(const f32x4 (&acc)[2][2][4][2], const Unit& u, int wr, int wc, int fr, int fq) const {
;     ...
;                     const int row = row0 + ai * HALF + m * 16;
;                     int fqo = fq; asm volatile("" : "+v"(fqo));
;                     f32x4 v[2][2]; float ss = 0.f;
; #pragma unroll
;                     for (int bj = 0; bj < 2; ++bj)
; #pragma unroll
;                         for (int n = 0; n < 2; ++n) { v[bj][n] = acc[ai][bj][m][n]; ss += (v[bj][n][0] * v[bj][n][0] + v[bj][n][1] * v[bj][n][1]) + (v[bj][n][2] * v[bj][n][2] + v[bj][n][3] * v[bj][n][3]); }
;                     ss += swz_xor<16>(ss); ss = xadd32(ss);
;                     const float rstd = __builtin_amdgcn_rsqf(ss * (1.0f / 64.0f) + EPS);
;                     const int t = row & (SEQ - 1); const float pos[2] = {(float)(t >> 6), (float)(t & 63)};
; #pragma unroll
;                     for (int bj = 0; bj < 2; ++bj) {
;                         u32x4 w;
; #pragma unroll
;                         for (int n = 0; n < 2; ++n) {
;                             f32x4 x = v[bj][n] * rstd * *(const f32x4*)(g + 32 * bj + 8 * fqo + 4 * n);
;                             if (latent) {
;                                 const float a0 = pos[bj] * fr0[n], a1 = pos[bj] * fr1[n];
;                                 const float c0 = __builtin_amdgcn_cosf(a0), s0 = __builtin_amdgcn_sinf(a0), c1 = __builtin_amdgcn_cosf(a1), s1 = __builtin_amdgcn_sinf(a1);
;                                 x = (f32x4){x[0] * c0 - x[1] * s0, x[1] * c0 + x[0] * s0, x[2] * c1 - x[3] * s1, x[3] * c1 + x[2] * s1};
;                             }
;                             if (n == 0) { w.x = cvt_pk_bf16(x[0], x[1]); w.y = cvt_pk_bf16(x[2], x[3]); } else { w.z = cvt_pk_bf16(x[0], x[1]); w.w = cvt_pk_bf16(x[2], x[3]); }
;                         }
;                         *(u32x4*)(dst + (size_t)row * 64 + 32 * bj + 8 * fq) = w;
.LBB0_477:
	v_cvt_pk_bf16_f32 v182, v182, v183
	v_cvt_pk_bf16_f32 v183, v184, v185
	v_cvt_pk_bf16_f32 v184, v186, v187
	v_cvt_pk_bf16_f32 v185, v188, v189
	global_store_dwordx4 v[180:181], v[182:185], off offset:64
	v_mul_f32_e32 v180, v86, v86
	v_mul_f32_e32 v181, v87, v87
	s_nop 0
	v_mul_f32_e32 v182, v84, v84
	v_mul_f32_e32 v183, v85, v85
	v_mul_f32_e32 v141, v64, v64
	v_pk_mov_b32 v[184:185], v[182:183], v[180:181] op_sel:[1,0]
	v_mov_b32_e32 v183, v181
	v_add_f32_e32 v180, v184, v182
	v_add_f32_e32 v181, v185, v183
	v_mul_f32_e32 v182, v82, v82
	v_mul_f32_e32 v183, v83, v83
	v_mul_f32_e32 v184, v80, v80
	v_mul_f32_e32 v185, v81, v81
	v_mul_f32_e32 v149, v65, v65
	v_pk_mov_b32 v[186:187], v[184:185], v[182:183] op_sel:[1,0]
	v_mov_b32_e32 v185, v183
	v_add_f32_e32 v182, v186, v184
	v_add_f32_e32 v183, v187, v185
	v_pk_add_f32 v[180:181], v[180:181], v[180:181] op_sel:[0,1] op_sel_hi:[1,0]
	v_pk_add_f32 v[182:183], v[182:183], v[182:183] op_sel:[0,1] op_sel_hi:[1,0]
	v_mov_b32_e32 v181, v141
	v_mov_b32_e32 v183, v149
	v_add_f32_e32 v180, v180, v182
	v_add_f32_e32 v181, v181, v183
	v_mul_f32_e32 v182, v69, v69
	v_mul_f32_e32 v184, v71, v71
	v_mul_f32_e32 v153, v66, v66
	v_mul_f32_e32 v155, v67, v67
	v_fma_f32 v183, v69, v69, v182
	v_fma_f32 v182, v68, v68, v182
	v_fma_f32 v185, v71, v71, v184
	v_fma_f32 v184, v70, v70, v184
	v_mov_b32_e32 v183, v153
	v_mov_b32_e32 v185, v155
	v_mov_b32_e32 v147, v236
	v_add_f32_e32 v182, v182, v184
	v_add_f32_e32 v183, v183, v185
	s_and_b64 vcc, exec, s[36:37]
	v_add_f32_e32 v180, v180, v182
	v_add_f32_e32 v181, v181, v183
	v_lshlrev_b32_e32 v182, 3, v147
	v_ashrrev_i32_e32 v183, 31, v182
	v_lshl_add_u64 v[188:189], v[182:183], 2, s[38:39]
	v_mov_b32_e32 v182, v246
	v_mov_b32_e32 v183, v247
	v_mov_b32_e32 v184, v248
	v_mov_b32_e32 v185, v249
	v_add_f32_e32 v141, v180, v181
	ds_swizzle_b32 v149, v141 offset:swizzle(SWAP,16)
	v_add_u32_e32 v180, 48, v140
	s_waitcnt lgkmcnt(0)
	v_add_f32_e32 v141, v141, v149
	v_mov_b32_e32 v149, v141
	s_nop 1
	v_permlane32_swap_b32_e32 v141, v149
	v_add_f32_e32 v141, v141, v149
	v_fmamk_f32 v141, v141, 0x3c800000, v193
	v_rsq_f32_e32 v186, v141
	v_bfe_u32 v141, v180, 6, 7
	v_cvt_f32_ubyte0_e32 v141, v141
	v_mul_f32_e32 v190, v84, v186
	v_mul_f32_e32 v191, v85, v186
	v_mul_f32_e32 v208, v86, v186
	v_mul_f32_e32 v209, v87, v186
	v_mul_f32_e32 v182, v182, v190
	v_mul_f32_e32 v183, v183, v191
	v_mul_f32_e32 v184, v184, v208
	v_mul_f32_e32 v185, v185, v209
	s_cbranch_vccnz .LBB0_479
	v_mul_f32_e32 v147, v194, v141
	v_sin_f32_e32 v208, v147
	v_mul_f32_e32 v149, v237, v141
	v_cos_f32_e32 v190, v147
	v_sin_f32_e32 v211, v149
	v_cos_f32_e32 v210, v149
	v_mul_f32_e32 v209, v208, v182
	v_mul_f32_e32 v208, v208, v183
	v_mul_f32_e32 v212, v190, v182
	v_mul_f32_e32 v213, v190, v183
	v_fma_f32 v182, v190, v182, v208
	v_fma_f32 v183, v190, v183, v209
	v_mul_f32_e32 v182, v211, v185
	v_fma_f32 v190, v210, v184, -v182
	v_fma_f32 v191, v211, v185, -v182
	v_mov_b32_e32 v214, v211
	v_mov_b32_e32 v215, v210
	v_mul_f32_e32 v182, v210, v185
	v_fma_f32 v210, v214, v184, v182
	v_fma_f32 v211, v215, v185, v182
	v_sub_f32_e32 v182, v212, v208
	v_mov_b32_e32 v184, v190
	v_mov_b32_e32 v185, v210
.LBB0_479:
	v_mov_b32_e32 v208, v250
	v_mov_b32_e32 v209, v251
	v_mov_b32_e32 v210, v200
	v_mov_b32_e32 v211, v201
	v_mov_b32_e32 v187, v186
	v_mov_b32_e32 v190, v186
	v_mov_b32_e32 v191, v186
	v_mul_f32_e32 v212, v82, v190
	v_mul_f32_e32 v213, v83, v191
	v_mul_f32_e32 v214, v80, v186
	v_mul_f32_e32 v215, v81, v187
	s_and_b64 vcc, exec, s[36:37]
	v_mul_f32_e32 v212, v212, v210
	v_mul_f32_e32 v213, v213, v211
	v_mul_f32_e32 v210, v214, v208
	v_mul_f32_e32 v211, v215, v209
	s_cbranch_vccnz .LBB0_481
	v_mul_f32_e32 v147, v238, v141
	v_sin_f32_e32 v214, v147
	v_mul_f32_e32 v141, v239, v141
	v_cos_f32_e32 v208, v147
	v_cos_f32_e32 v216, v141
	v_sin_f32_e32 v217, v141
	v_mul_f32_e32 v215, v214, v210
	v_mul_f32_e32 v214, v214, v211
	v_mul_f32_e32 v218, v208, v210
	v_mul_f32_e32 v219, v208, v211
	v_fma_f32 v210, v208, v210, v214
	v_fma_f32 v211, v208, v211, v215
	v_mul_f32_e32 v208, v217, v213
	v_mov_b32_e32 v220, v217
	v_mov_b32_e32 v221, v216
	v_mul_f32_e32 v210, v216, v213
	v_fma_f32 v209, v217, v213, -v208
	v_fma_f32 v208, v216, v212, -v208
	v_fma_f32 v216, v220, v212, v210
	v_fma_f32 v217, v221, v213, v210
	v_sub_f32_e32 v210, v218, v214
	v_mov_b32_e32 v212, v208
	v_mov_b32_e32 v213, v216

; __device__ __forceinline__ unsigned cvt_pk_bf16(float lo, float hi) { const f32x2 v = {lo, hi}; const bf16x2_t b = __builtin_convertvector(v, bf16x2_t); return __builtin_bit_cast(unsigned, b); }
; template <int M> __device__ __forceinline__ float swz_xor(float v) { return __builtin_bit_cast(float, __builtin_amdgcn_ds_swizzle(__builtin_bit_cast(int, v), (M << 10) | 0x1f)); }
;     __device__ __forceinline__ void operator()(const f32x4 (&acc)[2][2][4][2], const Unit& u, int wr, int wc, int fr, int fq) const {
;     ...
;                     int fqo = fq; asm volatile("" : "+v"(fqo));
;                     f32x4 v[2][2]; float ss = 0.f;
; #pragma unroll
;                     for (int bj = 0; bj < 2; ++bj)
; #pragma unroll
;                         for (int n = 0; n < 2; ++n) { v[bj][n] = acc[ai][bj][m][n]; ss += (v[bj][n][0] * v[bj][n][0] + v[bj][n][1] * v[bj][n][1]) + (v[bj][n][2] * v[bj][n][2] + v[bj][n][3] * v[bj][n][3]); }
;                     ss += swz_xor<16>(ss); ss = xadd32(ss);
;                     const float rstd = __builtin_amdgcn_rsqf(ss * (1.0f / 64.0f) + EPS);
;                     const int t = row & (SEQ - 1); const float pos[2] = {(float)(t >> 6), (float)(t & 63)};
; #pragma unroll
;                     for (int bj = 0; bj < 2; ++bj) {
;                         u32x4 w;
; #pragma unroll
;                         for (int n = 0; n < 2; ++n) {
;                             f32x4 x = v[bj][n] * rstd * *(const f32x4*)(g + 32 * bj + 8 * fqo + 4 * n);
;                             if (latent) {
;                                 const float a0 = pos[bj] * fr0[n], a1 = pos[bj] * fr1[n];
;                                 const float c0 = __builtin_amdgcn_cosf(a0), s0 = __builtin_amdgcn_sinf(a0), c1 = __builtin_amdgcn_cosf(a1), s1 = __builtin_amdgcn_sinf(a1);
;                                 x = (f32x4){x[0] * c0 - x[1] * s0, x[1] * c0 + x[0] * s0, x[2] * c1 - x[3] * s1, x[3] * c1 + x[2] * s1};
;                             }
;                             if (n == 0) { w.x = cvt_pk_bf16(x[0], x[1]); w.y = cvt_pk_bf16(x[2], x[3]); } else { w.z = cvt_pk_bf16(x[0], x[1]); w.w = cvt_pk_bf16(x[2], x[3]); }
;                         }
;                         *(u32x4*)(dst + (size_t)row * 64 + 32 * bj + 8 * fq) = w;
.LBB0_485:
	v_cvt_pk_bf16_f32 v210, v210, v211
	v_cvt_pk_bf16_f32 v211, v212, v213
	v_cvt_pk_bf16_f32 v212, v214, v215
	v_cvt_pk_bf16_f32 v213, v216, v217
	global_store_dwordx4 v[208:209], v[210:213], off offset:64
	v_mul_f32_e32 v208, v62, v62
	v_mul_f32_e32 v209, v63, v63
	s_nop 0
	v_mul_f32_e32 v212, v60, v60
	v_mul_f32_e32 v213, v61, v61
	v_mul_f32_e32 v141, v40, v40
	v_pk_mov_b32 v[214:215], v[212:213], v[208:209] op_sel:[1,0]
	v_mov_b32_e32 v213, v209
	v_add_f32_e32 v208, v214, v212
	v_add_f32_e32 v209, v215, v213
	v_mul_f32_e32 v212, v58, v58
	v_mul_f32_e32 v213, v59, v59
	v_mul_f32_e32 v214, v56, v56
	v_mul_f32_e32 v215, v57, v57
	v_mul_f32_e32 v149, v41, v41
	v_pk_mov_b32 v[216:217], v[214:215], v[212:213] op_sel:[1,0]
	v_mov_b32_e32 v215, v213
	v_add_f32_e32 v212, v216, v214
	v_add_f32_e32 v213, v217, v215
	v_pk_add_f32 v[208:209], v[208:209], v[208:209] op_sel:[0,1] op_sel_hi:[1,0]
	v_pk_add_f32 v[212:213], v[212:213], v[212:213] op_sel:[0,1] op_sel_hi:[1,0]
	v_mov_b32_e32 v209, v141
	v_mov_b32_e32 v213, v149
	v_add_f32_e32 v208, v208, v212
	v_add_f32_e32 v209, v209, v213
	v_mul_f32_e32 v212, v45, v45
	v_mul_f32_e32 v214, v47, v47
	v_mul_f32_e32 v153, v42, v42
	v_mul_f32_e32 v155, v43, v43
	v_fma_f32 v213, v45, v45, v212
	v_fma_f32 v212, v44, v44, v212
	v_fma_f32 v215, v47, v47, v214
	v_fma_f32 v214, v46, v46, v214
	v_mov_b32_e32 v213, v153
	v_mov_b32_e32 v215, v155
	v_mov_b32_e32 v147, v236
	v_add_f32_e32 v212, v212, v214
	v_add_f32_e32 v213, v213, v215
	v_add_u32_e32 v210, 0x80, v140
	v_add_f32_e32 v208, v208, v212
	v_add_f32_e32 v209, v209, v213
	v_lshlrev_b32_e32 v212, 3, v147
	v_ashrrev_i32_e32 v213, 31, v212
	v_lshl_add_u64 v[212:213], v[212:213], 2, s[38:39]
	v_mov_b32_e32 v214, v246
	v_mov_b32_e32 v215, v247
	v_mov_b32_e32 v216, v248
	v_mov_b32_e32 v217, v249
	v_add_f32_e32 v141, v208, v209
	ds_swizzle_b32 v149, v141 offset:swizzle(SWAP,16)
	s_and_b64 vcc, exec, s[36:37]
	s_waitcnt lgkmcnt(0)
	v_add_f32_e32 v141, v141, v149
	v_mov_b32_e32 v149, v141
	s_nop 1
	v_permlane32_swap_b32_e32 v141, v149
	v_add_f32_e32 v141, v141, v149
	v_fmamk_f32 v141, v141, 0x3c800000, v193
	v_rsq_f32_e32 v208, v141
	v_bfe_u32 v141, v210, 6, 7
	v_cvt_f32_ubyte0_e32 v141, v141
	v_mul_f32_e32 v218, v60, v208
	v_mul_f32_e32 v219, v61, v208
	v_mul_f32_e32 v220, v62, v208
	v_mul_f32_e32 v221, v63, v208
	v_mul_f32_e32 v214, v214, v218
	v_mul_f32_e32 v215, v215, v219
	v_mul_f32_e32 v216, v216, v220
	v_mul_f32_e32 v217, v217, v221
	s_cbranch_vccnz .LBB0_487
	v_mul_f32_e32 v147, v194, v141
	v_sin_f32_e32 v220, v147
	v_mul_f32_e32 v149, v237, v141
	v_cos_f32_e32 v218, v147
	v_sin_f32_e32 v223, v149
	v_cos_f32_e32 v222, v149
	v_mul_f32_e32 v221, v220, v214
	v_mul_f32_e32 v220, v220, v215
	v_mul_f32_e32 v226, v218, v214
	v_mul_f32_e32 v227, v218, v215
	v_fma_f32 v214, v218, v214, v220
	v_fma_f32 v215, v218, v215, v221
	v_mul_f32_e32 v214, v223, v217
	v_fma_f32 v218, v222, v216, -v214
	v_fma_f32 v219, v223, v217, -v214
	v_mov_b32_e32 v228, v223
	v_mov_b32_e32 v229, v222
	v_mul_f32_e32 v214, v222, v217
	v_fma_f32 v222, v228, v216, v214
	v_fma_f32 v223, v229, v217, v214
	v_sub_f32_e32 v214, v226, v220
	v_mov_b32_e32 v216, v218
	v_mov_b32_e32 v217, v222
.LBB0_487:
	v_mov_b32_e32 v220, v250
	v_mov_b32_e32 v221, v251
	v_mov_b32_e32 v222, v200
	v_mov_b32_e32 v223, v201
	v_mov_b32_e32 v209, v208
	v_mov_b32_e32 v218, v208
	v_mov_b32_e32 v219, v208
	v_mul_f32_e32 v226, v58, v218
	v_mul_f32_e32 v227, v59, v219
	v_mul_f32_e32 v228, v56, v208
	v_mul_f32_e32 v229, v57, v209
	s_and_b64 vcc, exec, s[36:37]
	v_mul_f32_e32 v222, v226, v222
	v_mul_f32_e32 v223, v227, v223
	v_mul_f32_e32 v220, v228, v220
	v_mul_f32_e32 v221, v229, v221
	s_cbranch_vccnz .LBB0_489
	v_mul_f32_e32 v147, v238, v141
	v_sin_f32_e32 v228, v147
	v_mul_f32_e32 v141, v239, v141
	v_cos_f32_e32 v226, v147
	v_sin_f32_e32 v241, v141
	v_cos_f32_e32 v240, v141
	v_mul_f32_e32 v229, v228, v220
	v_mul_f32_e32 v228, v228, v221
	v_mul_f32_e32 v242, v226, v220
	v_mul_f32_e32 v243, v226, v221
	v_fma_f32 v220, v226, v220, v228
	v_fma_f32 v221, v226, v221, v229
	v_mul_f32_e32 v220, v241, v223
	v_fma_f32 v226, v240, v222, -v220
	v_fma_f32 v227, v241, v223, -v220
	v_mov_b32_e32 v244, v241
	v_mov_b32_e32 v245, v240
	v_mul_f32_e32 v220, v240, v223
	v_fma_f32 v240, v244, v222, v220
	v_fma_f32 v241, v245, v223, v220
	v_sub_f32_e32 v220, v242, v228
	v_mov_b32_e32 v222, v226
	v_mov_b32_e32 v223, v240

; __device__ __forceinline__ unsigned cvt_pk_bf16(float lo, float hi) { const f32x2 v = {lo, hi}; const bf16x2_t b = __builtin_convertvector(v, bf16x2_t); return __builtin_bit_cast(unsigned, b); }
; template <int M> __device__ __forceinline__ float swz_xor(float v) { return __builtin_bit_cast(float, __builtin_amdgcn_ds_swizzle(__builtin_bit_cast(int, v), (M << 10) | 0x1f)); }
;     __device__ __forceinline__ void operator()(const f32x4 (&acc)[2][2][4][2], const Unit& u, int wr, int wc, int fr, int fq) const {
;     ...
;                     int fqo = fq; asm volatile("" : "+v"(fqo));
;                     f32x4 v[2][2]; float ss = 0.f;
; #pragma unroll
;                     for (int bj = 0; bj < 2; ++bj)
; #pragma unroll
;                         for (int n = 0; n < 2; ++n) { v[bj][n] = acc[ai][bj][m][n]; ss += (v[bj][n][0] * v[bj][n][0] + v[bj][n][1] * v[bj][n][1]) + (v[bj][n][2] * v[bj][n][2] + v[bj][n][3] * v[bj][n][3]); }
;                     ss += swz_xor<16>(ss); ss = xadd32(ss);
;                     const float rstd = __builtin_amdgcn_rsqf(ss * (1.0f / 64.0f) + EPS);
;                     const int t = row & (SEQ - 1); const float pos[2] = {(float)(t >> 6), (float)(t & 63)};
; #pragma unroll
;                     for (int bj = 0; bj < 2; ++bj) {
;                         u32x4 w;
; #pragma unroll
;                         for (int n = 0; n < 2; ++n) {
;                             f32x4 x = v[bj][n] * rstd * *(const f32x4*)(g + 32 * bj + 8 * fqo + 4 * n);
;                             if (latent) {
;                                 const float a0 = pos[bj] * fr0[n], a1 = pos[bj] * fr1[n];
;                                 const float c0 = __builtin_amdgcn_cosf(a0), s0 = __builtin_amdgcn_sinf(a0), c1 = __builtin_amdgcn_cosf(a1), s1 = __builtin_amdgcn_sinf(a1);
;                                 x = (f32x4){x[0] * c0 - x[1] * s0, x[1] * c0 + x[0] * s0, x[2] * c1 - x[3] * s1, x[3] * c1 + x[2] * s1};
;                             }
;                             if (n == 0) { w.x = cvt_pk_bf16(x[0], x[1]); w.y = cvt_pk_bf16(x[2], x[3]); } else { w.z = cvt_pk_bf16(x[0], x[1]); w.w = cvt_pk_bf16(x[2], x[3]); }
;                         }
;                         *(u32x4*)(dst + (size_t)row * 64 + 32 * bj + 8 * fq) = w;
.LBB0_493:
	v_cvt_pk_bf16_f32 v148, v214, v215
	v_cvt_pk_bf16_f32 v149, v216, v217
	v_cvt_pk_bf16_f32 v150, v144, v145
	v_cvt_pk_bf16_f32 v151, v146, v147
	global_store_dwordx4 v[210:211], v[148:151], off offset:64
	v_mul_f32_e32 v144, v54, v54
	v_mul_f32_e32 v145, v55, v55
	v_mul_f32_e32 v146, v52, v52
	v_mul_f32_e32 v147, v53, v53
	v_mul_f32_e32 v141, v24, v24
	v_pk_mov_b32 v[148:149], v[146:147], v[144:145] op_sel:[1,0]
	v_mov_b32_e32 v147, v145
	v_add_f32_e32 v144, v148, v146
	v_add_f32_e32 v145, v149, v147
	v_mul_f32_e32 v146, v50, v50
	v_mul_f32_e32 v147, v51, v51
	v_mul_f32_e32 v148, v48, v48
	v_mul_f32_e32 v149, v49, v49
	v_pk_add_f32 v[144:145], v[144:145], v[144:145] op_sel:[0,1] op_sel_hi:[1,0]
	v_pk_mov_b32 v[150:151], v[148:149], v[146:147] op_sel:[1,0]
	v_mov_b32_e32 v149, v147
	v_add_f32_e32 v146, v150, v148
	v_add_f32_e32 v147, v151, v149
	v_mul_f32_e32 v148, v25, v25
	v_pk_add_f32 v[146:147], v[146:147], v[146:147] op_sel:[0,1] op_sel_hi:[1,0]
	v_mov_b32_e32 v145, v141
	v_mov_b32_e32 v147, v148
	v_add_f32_e32 v144, v144, v146
	v_add_f32_e32 v145, v145, v147
	v_mul_f32_e32 v146, v29, v29
	v_mul_f32_e32 v149, v26, v26
	v_fma_f32 v147, v29, v29, v146
	v_fma_f32 v146, v28, v28, v146
	v_mul_f32_e32 v148, v31, v31
	v_mul_f32_e32 v150, v27, v27
	v_mov_b32_e32 v147, v149
	v_fma_f32 v149, v31, v31, v148
	v_fma_f32 v148, v30, v30, v148
	v_mov_b32_e32 v152, v236
	v_mov_b32_e32 v149, v150
	v_add_f32_e32 v146, v146, v148
	v_add_f32_e32 v147, v147, v149
	v_lshlrev_b32_e32 v148, 3, v152
	v_ashrrev_i32_e32 v149, 31, v148
	v_lshl_add_u64 v[148:149], v[148:149], 2, s[38:39]
	v_mov_b32_e32 v150, v246
	v_mov_b32_e32 v151, v247
	v_mov_b32_e32 v152, v248
	v_mov_b32_e32 v153, v249
	v_add_f32_e32 v144, v144, v146
	v_add_f32_e32 v145, v145, v147
	v_add_u32_e32 v146, 0x90, v140
	v_add_f32_e32 v141, v144, v145
	ds_swizzle_b32 v144, v141 offset:swizzle(SWAP,16)
	s_and_b64 vcc, exec, s[36:37]
	s_waitcnt lgkmcnt(0)
	v_add_f32_e32 v141, v141, v144
	v_mov_b32_e32 v144, v141
	s_nop 1
	v_permlane32_swap_b32_e32 v141, v144
	v_add_f32_e32 v141, v141, v144
	v_fmamk_f32 v141, v141, 0x3c800000, v193
	v_rsq_f32_e32 v144, v141
	v_bfe_u32 v141, v146, 6, 7
	v_cvt_f32_ubyte0_e32 v141, v141
	v_mul_f32_e32 v154, v52, v144
	v_mul_f32_e32 v155, v53, v144
	v_mul_f32_e32 v208, v54, v144
	v_mul_f32_e32 v209, v55, v144
	v_mul_f32_e32 v150, v150, v154
	v_mul_f32_e32 v151, v151, v155
	v_mul_f32_e32 v152, v152, v208
	v_mul_f32_e32 v153, v153, v209
	s_cbranch_vccnz .LBB0_495
	v_mul_f32_e32 v145, v194, v141
	v_sin_f32_e32 v208, v145
	v_mul_f32_e32 v147, v237, v141
	v_cos_f32_e32 v154, v145
	v_sin_f32_e32 v211, v147
	v_cos_f32_e32 v210, v147
	v_mul_f32_e32 v209, v208, v150
	v_mul_f32_e32 v208, v208, v151
	v_mul_f32_e32 v212, v154, v150
	v_mul_f32_e32 v213, v154, v151
	v_fma_f32 v150, v154, v150, v208
	v_fma_f32 v151, v154, v151, v209
	v_mul_f32_e32 v150, v211, v153
	v_fma_f32 v154, v210, v152, -v150
	v_fma_f32 v155, v211, v153, -v150
	v_mov_b32_e32 v214, v211
	v_mov_b32_e32 v215, v210
	v_mul_f32_e32 v150, v210, v153
	v_fma_f32 v210, v214, v152, v150
	v_fma_f32 v211, v215, v153, v150
	v_sub_f32_e32 v150, v212, v208
	v_mov_b32_e32 v152, v154
	v_mov_b32_e32 v153, v210
.LBB0_495:
	v_mov_b32_e32 v208, v250
	v_mov_b32_e32 v209, v251
	v_mov_b32_e32 v210, v200
	v_mov_b32_e32 v211, v201
	v_mov_b32_e32 v145, v144
	v_mov_b32_e32 v154, v144
	v_mov_b32_e32 v155, v144
	v_mul_f32_e32 v212, v50, v154
	v_mul_f32_e32 v213, v51, v155
	v_mul_f32_e32 v214, v48, v144
	v_mul_f32_e32 v215, v49, v145
	s_and_b64 vcc, exec, s[36:37]
	v_mul_f32_e32 v210, v212, v210
	v_mul_f32_e32 v211, v213, v211
	v_mul_f32_e32 v208, v214, v208
	v_mul_f32_e32 v209, v215, v209
	s_cbranch_vccnz .LBB0_497
	v_mul_f32_e32 v147, v238, v141
	v_sin_f32_e32 v214, v147
	v_mul_f32_e32 v141, v239, v141
	v_cos_f32_e32 v212, v147
	v_sin_f32_e32 v217, v141
	v_cos_f32_e32 v216, v141
	v_mul_f32_e32 v215, v214, v208
	v_mul_f32_e32 v214, v214, v209
	v_mul_f32_e32 v218, v212, v208
	v_mul_f32_e32 v219, v212, v209
	v_fma_f32 v208, v212, v208, v214
	v_fma_f32 v209, v212, v209, v215
	v_mul_f32_e32 v208, v217, v211
	v_fma_f32 v212, v216, v210, -v208
	v_fma_f32 v213, v217, v211, -v208
	v_mov_b32_e32 v220, v217
	v_mov_b32_e32 v221, v216
	v_mul_f32_e32 v208, v216, v211
	v_fma_f32 v216, v220, v210, v208
	v_fma_f32 v217, v221, v211, v208
	v_sub_f32_e32 v208, v218, v214
	v_mov_b32_e32 v210, v212
	v_mov_b32_e32 v211, v216

; __device__ __forceinline__ unsigned cvt_pk_bf16(float lo, float hi) { const f32x2 v = {lo, hi}; const bf16x2_t b = __builtin_convertvector(v, bf16x2_t); return __builtin_bit_cast(unsigned, b); }
; template <int M> __device__ __forceinline__ float swz_xor(float v) { return __builtin_bit_cast(float, __builtin_amdgcn_ds_swizzle(__builtin_bit_cast(int, v), (M << 10) | 0x1f)); }
;     __device__ __forceinline__ void operator()(const f32x4 (&acc)[2][2][4][2], const Unit& u, int wr, int wc, int fr, int fq) const {
;     ...
;                     int fqo = fq; asm volatile("" : "+v"(fqo));
;                     f32x4 v[2][2]; float ss = 0.f;
; #pragma unroll
;                     for (int bj = 0; bj < 2; ++bj)
; #pragma unroll
;                         for (int n = 0; n < 2; ++n) { v[bj][n] = acc[ai][bj][m][n]; ss += (v[bj][n][0] * v[bj][n][0] + v[bj][n][1] * v[bj][n][1]) + (v[bj][n][2] * v[bj][n][2] + v[bj][n][3] * v[bj][n][3]); }
;                     ss += swz_xor<16>(ss); ss = xadd32(ss);
;                     const float rstd = __builtin_amdgcn_rsqf(ss * (1.0f / 64.0f) + EPS);
;                     const int t = row & (SEQ - 1); const float pos[2] = {(float)(t >> 6), (float)(t & 63)};
; #pragma unroll
;                     for (int bj = 0; bj < 2; ++bj) {
;                         u32x4 w;
; #pragma unroll
;                         for (int n = 0; n < 2; ++n) {
;                             f32x4 x = v[bj][n] * rstd * *(const f32x4*)(g + 32 * bj + 8 * fqo + 4 * n);
;                             if (latent) {
;                                 const float a0 = pos[bj] * fr0[n], a1 = pos[bj] * fr1[n];
;                                 const float c0 = __builtin_amdgcn_cosf(a0), s0 = __builtin_amdgcn_sinf(a0), c1 = __builtin_amdgcn_cosf(a1), s1 = __builtin_amdgcn_sinf(a1);
;                                 x = (f32x4){x[0] * c0 - x[1] * s0, x[1] * c0 + x[0] * s0, x[2] * c1 - x[3] * s1, x[3] * c1 + x[2] * s1};
;                             }
;                             if (n == 0) { w.x = cvt_pk_bf16(x[0], x[1]); w.y = cvt_pk_bf16(x[2], x[3]); } else { w.z = cvt_pk_bf16(x[0], x[1]); w.w = cvt_pk_bf16(x[2], x[3]); }
;                         }
;                         *(u32x4*)(dst + (size_t)row * 64 + 32 * bj + 8 * fq) = w;
.LBB0_501:
	v_cvt_pk_bf16_f32 v150, v150, v151
	v_cvt_pk_bf16_f32 v151, v152, v153
	v_cvt_pk_bf16_f32 v152, v144, v145
	v_cvt_pk_bf16_f32 v153, v148, v149
	global_store_dwordx4 v[146:147], v[150:153], off offset:64
	v_mul_f32_e32 v144, v38, v38
	v_mul_f32_e32 v145, v39, v39
	v_mul_f32_e32 v146, v36, v36
	v_mul_f32_e32 v147, v37, v37
	v_mul_f32_e32 v141, v8, v8
	v_pk_mov_b32 v[148:149], v[146:147], v[144:145] op_sel:[1,0]
	v_mov_b32_e32 v147, v145
	v_add_f32_e32 v144, v148, v146
	v_add_f32_e32 v145, v149, v147
	v_mul_f32_e32 v146, v34, v34
	v_mul_f32_e32 v147, v35, v35
	v_mul_f32_e32 v148, v32, v32
	v_mul_f32_e32 v149, v33, v33
	v_pk_add_f32 v[144:145], v[144:145], v[144:145] op_sel:[0,1] op_sel_hi:[1,0]
	v_pk_mov_b32 v[150:151], v[148:149], v[146:147] op_sel:[1,0]
	v_mov_b32_e32 v149, v147
	v_add_f32_e32 v146, v150, v148
	v_add_f32_e32 v147, v151, v149
	v_mul_f32_e32 v148, v9, v9
	v_pk_add_f32 v[146:147], v[146:147], v[146:147] op_sel:[0,1] op_sel_hi:[1,0]
	v_mov_b32_e32 v145, v141
	v_mov_b32_e32 v147, v148
	v_add_f32_e32 v144, v144, v146
	v_add_f32_e32 v145, v145, v147
	v_mul_f32_e32 v146, v13, v13
	v_mul_f32_e32 v149, v10, v10
	v_fma_f32 v147, v13, v13, v146
	v_fma_f32 v146, v12, v12, v146
	v_mul_f32_e32 v148, v15, v15
	v_mul_f32_e32 v150, v11, v11
	v_mov_b32_e32 v147, v149
	v_fma_f32 v149, v15, v15, v148
	v_fma_f32 v148, v14, v14, v148
	v_mov_b32_e32 v152, v236
	v_mov_b32_e32 v149, v150
	v_add_f32_e32 v146, v146, v148
	v_add_f32_e32 v147, v147, v149
	v_lshlrev_b32_e32 v148, 3, v152
	v_ashrrev_i32_e32 v149, 31, v148
	v_lshl_add_u64 v[148:149], v[148:149], 2, s[38:39]
	v_mov_b32_e32 v150, v246
	v_mov_b32_e32 v151, v247
	v_mov_b32_e32 v152, v248
	v_mov_b32_e32 v153, v249
	v_add_f32_e32 v144, v144, v146
	v_add_f32_e32 v145, v145, v147
	v_add_u32_e32 v146, 0xa0, v140
	v_add_f32_e32 v141, v144, v145
	ds_swizzle_b32 v144, v141 offset:swizzle(SWAP,16)
	s_and_b64 vcc, exec, s[36:37]
	s_waitcnt lgkmcnt(0)
	v_add_f32_e32 v141, v141, v144
	v_mov_b32_e32 v144, v141
	s_nop 1
	v_permlane32_swap_b32_e32 v141, v144
	v_add_f32_e32 v141, v141, v144
	v_fmamk_f32 v141, v141, 0x3c800000, v193
	v_rsq_f32_e32 v144, v141
	v_bfe_u32 v141, v146, 6, 7
	v_cvt_f32_ubyte0_e32 v141, v141
	v_mul_f32_e32 v154, v36, v144
	v_mul_f32_e32 v155, v37, v144
	v_mul_f32_e32 v156, v38, v144
	v_mul_f32_e32 v157, v39, v144
	v_mul_f32_e32 v150, v150, v154
	v_mul_f32_e32 v151, v151, v155
	v_mul_f32_e32 v152, v152, v156
	v_mul_f32_e32 v153, v153, v157
	s_cbranch_vccnz .LBB0_503
	v_mul_f32_e32 v145, v194, v141
	v_sin_f32_e32 v156, v145
	v_mul_f32_e32 v147, v237, v141
	v_cos_f32_e32 v154, v145
	v_sin_f32_e32 v159, v147
	v_cos_f32_e32 v158, v147
	v_mul_f32_e32 v157, v156, v150
	v_mul_f32_e32 v156, v156, v151
	v_mul_f32_e32 v160, v154, v150
	v_mul_f32_e32 v161, v154, v151
	v_fma_f32 v150, v154, v150, v156
	v_fma_f32 v151, v154, v151, v157
	v_mul_f32_e32 v150, v159, v153
	v_fma_f32 v154, v158, v152, -v150
	v_fma_f32 v155, v159, v153, -v150
	v_mov_b32_e32 v162, v159
	v_mov_b32_e32 v163, v158
	v_mul_f32_e32 v150, v158, v153
	v_fma_f32 v158, v162, v152, v150
	v_fma_f32 v159, v163, v153, v150
	v_sub_f32_e32 v150, v160, v156
	v_mov_b32_e32 v152, v154
	v_mov_b32_e32 v153, v158
.LBB0_503:
	v_mov_b32_e32 v156, v250
	v_mov_b32_e32 v157, v251
	v_mov_b32_e32 v158, v200
	v_mov_b32_e32 v159, v201
	v_mov_b32_e32 v145, v144
	v_mov_b32_e32 v154, v144
	v_mov_b32_e32 v155, v144
	v_mul_f32_e32 v160, v34, v154
	v_mul_f32_e32 v161, v35, v155
	v_mul_f32_e32 v162, v32, v144
	v_mul_f32_e32 v163, v33, v145
	s_and_b64 vcc, exec, s[36:37]
	v_mul_f32_e32 v158, v160, v158
	v_mul_f32_e32 v159, v161, v159
	v_mul_f32_e32 v156, v162, v156
	v_mul_f32_e32 v157, v163, v157
	s_cbranch_vccnz .LBB0_505
	v_mul_f32_e32 v147, v238, v141
	v_sin_f32_e32 v162, v147
	v_mul_f32_e32 v141, v239, v141
	v_cos_f32_e32 v160, v147
	v_sin_f32_e32 v165, v141
	v_cos_f32_e32 v164, v141
	v_mul_f32_e32 v163, v162, v156
	v_mul_f32_e32 v162, v162, v157
	v_mul_f32_e32 v166, v160, v156
	v_mul_f32_e32 v167, v160, v157
	v_fma_f32 v156, v160, v156, v162
	v_fma_f32 v157, v160, v157, v163
	v_mul_f32_e32 v156, v165, v159
	v_fma_f32 v160, v164, v158, -v156
	v_fma_f32 v161, v165, v159, -v156
	v_mov_b32_e32 v208, v165
	v_mov_b32_e32 v209, v164
	v_mul_f32_e32 v156, v164, v159
	v_fma_f32 v164, v208, v158, v156
	v_fma_f32 v165, v209, v159, v156
	v_sub_f32_e32 v156, v166, v162
	v_mov_b32_e32 v158, v160
	v_mov_b32_e32 v159, v164

; __device__ __forceinline__ unsigned cvt_pk_bf16(float lo, float hi) { const f32x2 v = {lo, hi}; const bf16x2_t b = __builtin_convertvector(v, bf16x2_t); return __builtin_bit_cast(unsigned, b); }
; template <int M> __device__ __forceinline__ float swz_xor(float v) { return __builtin_bit_cast(float, __builtin_amdgcn_ds_swizzle(__builtin_bit_cast(int, v), (M << 10) | 0x1f)); }
;     __device__ __forceinline__ void operator()(const f32x4 (&acc)[2][2][4][2], const Unit& u, int wr, int wc, int fr, int fq) const {
;     ...
;                     int fqo = fq; asm volatile("" : "+v"(fqo));
;                     f32x4 v[2][2]; float ss = 0.f;
; #pragma unroll
;                     for (int bj = 0; bj < 2; ++bj)
; #pragma unroll
;                         for (int n = 0; n < 2; ++n) { v[bj][n] = acc[ai][bj][m][n]; ss += (v[bj][n][0] * v[bj][n][0] + v[bj][n][1] * v[bj][n][1]) + (v[bj][n][2] * v[bj][n][2] + v[bj][n][3] * v[bj][n][3]); }
;                     ss += swz_xor<16>(ss); ss = xadd32(ss);
;                     const float rstd = __builtin_amdgcn_rsqf(ss * (1.0f / 64.0f) + EPS);
;                     const int t = row & (SEQ - 1); const float pos[2] = {(float)(t >> 6), (float)(t & 63)};
; #pragma unroll
;                     for (int bj = 0; bj < 2; ++bj) {
;                         u32x4 w;
; #pragma unroll
;                         for (int n = 0; n < 2; ++n) {
;                             f32x4 x = v[bj][n] * rstd * *(const f32x4*)(g + 32 * bj + 8 * fqo + 4 * n);
;                             if (latent) {
;                                 const float a0 = pos[bj] * fr0[n], a1 = pos[bj] * fr1[n];
;                                 const float c0 = __builtin_amdgcn_cosf(a0), s0 = __builtin_amdgcn_sinf(a0), c1 = __builtin_amdgcn_cosf(a1), s1 = __builtin_amdgcn_sinf(a1);
;                                 x = (f32x4){x[0] * c0 - x[1] * s0, x[1] * c0 + x[0] * s0, x[2] * c1 - x[3] * s1, x[3] * c1 + x[2] * s1};
;                             }
;                             if (n == 0) { w.x = cvt_pk_bf16(x[0], x[1]); w.y = cvt_pk_bf16(x[2], x[3]); } else { w.z = cvt_pk_bf16(x[0], x[1]); w.w = cvt_pk_bf16(x[2], x[3]); }
;                         }
;                         *(u32x4*)(dst + (size_t)row * 64 + 32 * bj + 8 * fq) = w;
.LBB0_509:
	v_cvt_pk_bf16_f32 v150, v150, v151
	v_cvt_pk_bf16_f32 v151, v152, v153
	v_cvt_pk_bf16_f32 v152, v144, v145
	v_cvt_pk_bf16_f32 v153, v148, v149
	global_store_dwordx4 v[146:147], v[150:153], off offset:64
	v_mul_f32_e32 v144, v22, v22
	v_mul_f32_e32 v145, v23, v23
	v_mul_f32_e32 v146, v20, v20
	v_mul_f32_e32 v147, v21, v21
	v_mov_b32_e32 v141, v236
	v_pk_mov_b32 v[148:149], v[146:147], v[144:145] op_sel:[1,0]
	v_mov_b32_e32 v147, v145
	v_add_f32_e32 v144, v148, v146
	v_add_f32_e32 v145, v149, v147
	v_mul_f32_e32 v146, v18, v18
	v_mul_f32_e32 v147, v19, v19
	v_mul_f32_e32 v148, v16, v16
	v_mul_f32_e32 v149, v17, v17
	v_pk_add_f32 v[144:145], v[144:145], v[144:145] op_sel:[0,1] op_sel_hi:[1,0]
	v_pk_mov_b32 v[150:151], v[148:149], v[146:147] op_sel:[1,0]
	v_mov_b32_e32 v149, v147
	v_add_f32_e32 v146, v150, v148
	v_add_f32_e32 v147, v151, v149
	v_mul_f32_e32 v148, v0, v0
	v_mul_f32_e32 v149, v1, v1
	v_pk_add_f32 v[146:147], v[146:147], v[146:147] op_sel:[0,1] op_sel_hi:[1,0]
	v_mov_b32_e32 v145, v148
	v_mov_b32_e32 v147, v149
	v_add_f32_e32 v144, v144, v146
	v_add_f32_e32 v145, v145, v147
	v_mul_f32_e32 v146, v5, v5
	v_mul_f32_e32 v148, v7, v7
	v_mul_f32_e32 v150, v2, v2
	v_mul_f32_e32 v151, v3, v3
	v_fma_f32 v147, v5, v5, v146
	v_fma_f32 v146, v4, v4, v146
	v_fma_f32 v149, v7, v7, v148
	v_fma_f32 v148, v6, v6, v148
	v_mov_b32_e32 v147, v150
	v_mov_b32_e32 v149, v151
	v_add_f32_e32 v146, v146, v148
	v_add_f32_e32 v147, v147, v149
	s_and_b64 vcc, exec, s[36:37]
	v_add_f32_e32 v144, v144, v146
	v_add_f32_e32 v145, v145, v147
	v_lshlrev_b32_e32 v146, 3, v141
	v_ashrrev_i32_e32 v147, 31, v146
	v_lshl_add_u64 v[146:147], v[146:147], 2, s[38:39]
	v_mov_b32_e32 v148, v246
	v_mov_b32_e32 v149, v247
	v_mov_b32_e32 v150, v248
	v_mov_b32_e32 v151, v249
	v_add_f32_e32 v145, v144, v145
	v_add_u32_e32 v144, 0xb0, v140
	ds_swizzle_b32 v140, v145 offset:swizzle(SWAP,16)
	s_waitcnt lgkmcnt(0)
	v_add_f32_e32 v140, v145, v140
	v_mov_b32_e32 v145, v140
	s_nop 1
	v_permlane32_swap_b32_e32 v140, v145
	v_add_f32_e32 v140, v140, v145
	v_fmamk_f32 v140, v140, 0x3c800000, v193
	v_rsq_f32_e32 v140, v140
	v_bfe_u32 v145, v144, 6, 7
	v_cvt_f32_ubyte0_e32 v145, v145
	v_mul_f32_e32 v152, v20, v140
	v_mul_f32_e32 v153, v21, v140
	v_mul_f32_e32 v154, v22, v140
	v_mul_f32_e32 v155, v23, v140
	v_mul_f32_e32 v148, v148, v152
	v_mul_f32_e32 v149, v149, v153
	v_mul_f32_e32 v150, v150, v154
	v_mul_f32_e32 v151, v151, v155
	s_cbranch_vccnz .LBB0_511
	v_mul_f32_e32 v141, v194, v145
	v_sin_f32_e32 v154, v141
	v_mul_f32_e32 v153, v237, v145
	v_cos_f32_e32 v152, v141
	v_sin_f32_e32 v157, v153
	v_cos_f32_e32 v156, v153
	v_mul_f32_e32 v155, v154, v148
	v_mul_f32_e32 v154, v154, v149
	v_mul_f32_e32 v158, v152, v148
	v_mul_f32_e32 v159, v152, v149
	v_fma_f32 v148, v152, v148, v154
	v_fma_f32 v149, v152, v149, v155
	v_mul_f32_e32 v148, v157, v151
	v_fma_f32 v152, v156, v150, -v148
	v_fma_f32 v153, v157, v151, -v148
	v_mov_b32_e32 v160, v157
	v_mov_b32_e32 v161, v156
	v_mul_f32_e32 v148, v156, v151
	v_fma_f32 v156, v160, v150, v148
	v_fma_f32 v157, v161, v151, v148
	v_sub_f32_e32 v148, v158, v154
	v_mov_b32_e32 v150, v152
	v_mov_b32_e32 v151, v156
.LBB0_511:
	v_mov_b32_e32 v154, v250
	v_mov_b32_e32 v155, v251
	v_mov_b32_e32 v156, v200
	v_mov_b32_e32 v157, v201
	v_mov_b32_e32 v141, v140
	v_mov_b32_e32 v152, v140
	v_mov_b32_e32 v153, v140
	v_mul_f32_e32 v158, v18, v152
	v_mul_f32_e32 v159, v19, v153
	v_mul_f32_e32 v160, v16, v140
	v_mul_f32_e32 v161, v17, v141
	s_and_b64 vcc, exec, s[36:37]
	v_mul_f32_e32 v156, v158, v156
	v_mul_f32_e32 v157, v159, v157
	v_mul_f32_e32 v154, v160, v154
	v_mul_f32_e32 v155, v161, v155
	s_cbranch_vccnz .LBB0_513
	v_mul_f32_e32 v159, v238, v145
	v_sin_f32_e32 v160, v159
	v_mul_f32_e32 v145, v239, v145
	v_cos_f32_e32 v158, v159
	v_sin_f32_e32 v163, v145
	v_cos_f32_e32 v162, v145
	v_mul_f32_e32 v161, v160, v154
	v_mul_f32_e32 v160, v160, v155
	v_mul_f32_e32 v164, v158, v154
	v_mul_f32_e32 v165, v158, v155
	v_fma_f32 v154, v158, v154, v160
	v_fma_f32 v155, v158, v155, v161
	v_mul_f32_e32 v154, v163, v157
	v_fma_f32 v158, v162, v156, -v154
	v_fma_f32 v159, v163, v157, -v154
	v_mov_b32_e32 v166, v163
	v_mov_b32_e32 v167, v162
	v_mul_f32_e32 v154, v162, v157
	v_fma_f32 v162, v166, v156, v154
	v_fma_f32 v163, v167, v157, v154
	v_sub_f32_e32 v154, v164, v160
	v_mov_b32_e32 v156, v158
	v_mov_b32_e32 v157, v162
